# modulated rmsnorm phases: wave-wide sum of squares via DPP quad/row permutes and v_permlane16/32_swap instead of a 6-step ds_bpermute butterfly (on top of v66)
# speedup vs baseline: 1.0022x; 1.0022x over previous
.LBB0_210:
	v_add_u32_e32 v4, 0xffffe000, v40
	v_cmp_gt_i32_e32 vcc, s81, v40
	v_mov_b32_e32 v5, s11
	v_mov_b32_e32 v6, s9
	v_cndmask_b32_e32 v1, 0, v41, vcc
	v_cndmask_b32_e32 v0, v4, v40, vcc
	v_mov_b32_e32 v7, s10
	v_mov_b32_e32 v8, s8
	v_cndmask_b32_e32 v3, v5, v6, vcc
	v_cndmask_b32_e32 v2, v7, v8, vcc
	v_lshlrev_b64 v[0:1], 12, v[0:1]
	v_lshl_add_u64 v[0:1], v[2:3], 0, v[0:1]
	v_lshl_add_u64 v[0:1], v[0:1], 0, v[22:23]
	global_load_dwordx4 v[66:69], v[0:1], off
	global_load_dwordx4 v[16:19], v[0:1], off offset:3072
	global_load_dwordx4 v[70:73], v[0:1], off offset:1024
	global_load_dwordx4 v[74:77], v[0:1], off offset:2048
	v_lshrrev_b32_e32 v2, 12, v4
	v_add_u32_e32 v2, 1, v2
	v_mov_b64_e32 v[0:1], s[14:15]
	v_cndmask_b32_e64 v2, v2, 0, vcc
	v_mad_u64_u32 v[0:1], s[6:7], v2, s33, v[0:1]
	v_lshl_add_u64 v[90:91], v[0:1], 0, s[58:59]
	v_lshl_add_u64 v[2:3], v[90:91], 0, v[22:23]
	global_load_dwordx4 v[78:81], v[2:3], off
	global_load_dwordx4 v[82:85], v[24:25], off
	v_lshl_add_u64 v[92:93], v[0:1], 0, v[22:23]
	global_load_dwordx4 v[86:89], v[92:93], off
	v_lshl_add_u64 v[44:45], s[2:3], 0, v[40:41]
	v_cmp_gt_i32_e32 vcc, s33, v44
	v_mov_b32_e32 v33, v23
	v_lshl_add_u64 v[96:97], v[90:91], 0, v[32:33]
	s_waitcnt vmcnt(6)
	v_mul_f32_e32 v4, v67, v67
	v_fmac_f32_e32 v4, v66, v66
	v_fmac_f32_e32 v4, v68, v68
	v_fmac_f32_e32 v4, v69, v69
	s_waitcnt vmcnt(4)
	v_fmac_f32_e32 v4, v70, v70
	v_fmac_f32_e32 v4, v71, v71
	v_fmac_f32_e32 v4, v72, v72
	v_fmac_f32_e32 v4, v73, v73
	s_waitcnt vmcnt(3)
	v_fmac_f32_e32 v4, v74, v74
	v_fmac_f32_e32 v4, v75, v75
	v_fmac_f32_e32 v4, v76, v76
	v_pk_mul_f32 v[2:3], v[16:17], v[16:17]
	v_fmac_f32_e32 v4, v77, v77
	v_add_f32_e32 v2, v2, v4
	v_pk_mul_f32 v[0:1], v[18:19], v[18:19]
	v_add_f32_e32 v2, v3, v2
	v_add_f32_e32 v0, v0, v2
	v_add_f32_e32 v0, v1, v0
	ds_bpermute_b32 v1, v60, v0
	v_cndmask_b32_e32 v4, v40, v44, vcc
	v_add_u32_e32 v9, 0xffffe000, v4
	s_waitcnt vmcnt(2)
	v_pk_add_f32 v[78:79], v[78:79], 1.0 op_sel_hi:[1,0]
	v_pk_add_f32 v[80:81], v[80:81], 1.0 op_sel_hi:[1,0]
	s_waitcnt lgkmcnt(0)
	v_add_f32_e32 v2, v0, v1
	ds_bpermute_b32 v3, v61, v2
	v_lshl_add_u64 v[0:1], v[42:43], 0, v[26:27]
	v_add_co_u32_e64 v94, s[6:7], s83, v0
	v_ashrrev_i32_e32 v0, 31, v4
	s_waitcnt lgkmcnt(0)
	v_add_f32_e32 v2, v2, v3
	ds_bpermute_b32 v3, v62, v2
	v_addc_co_u32_e64 v95, s[6:7], 0, v1, s[6:7]
	v_cmp_gt_i32_e64 s[6:7], s81, v4
	s_waitcnt lgkmcnt(0)
	v_add_f32_e32 v2, v2, v3
	ds_bpermute_b32 v3, v63, v2
	v_cndmask_b32_e64 v1, 0, v0, s[6:7]
	v_cndmask_b32_e64 v0, v9, v4, s[6:7]
	v_lshlrev_b64 v[0:1], 12, v[0:1]
	s_waitcnt lgkmcnt(0)
	v_add_f32_e32 v4, v2, v3
	ds_bpermute_b32 v9, v64, v4
	v_cndmask_b32_e64 v3, v5, v6, s[6:7]
	v_cndmask_b32_e64 v2, v7, v8, s[6:7]
	v_lshl_add_u64 v[0:1], v[2:3], 0, v[0:1]
	v_lshl_add_u64 v[0:1], v[0:1], 0, v[22:23]
	s_waitcnt lgkmcnt(0)
	v_add_f32_e32 v2, v4, v9
	ds_bpermute_b32 v3, v65, v2
	global_load_dwordx4 v[12:15], v[0:1], off
	global_load_dwordx4 v[8:11], v[0:1], off offset:1024
	s_waitcnt lgkmcnt(0)
	v_add_f32_e32 v2, v2, v3
	v_fmamk_f32 v2, v2, 0x3a800000, v46
	v_mul_f32_e32 v3, 0x4b800000, v2
	v_cmp_gt_f32_e64 s[6:7], s82, v2
	s_nop 1
	v_cndmask_b32_e64 v2, v2, v3, s[6:7]
	v_rsq_f32_e32 v35, v2
	global_load_dwordx4 v[4:7], v[0:1], off offset:2048
	s_nop 0
	global_load_dwordx4 v[0:3], v[0:1], off offset:3072
	v_mul_f32_e32 v37, 0x45800000, v35
	v_cndmask_b32_e64 v98, v35, v37, s[6:7]
	v_pk_mul_f32 v[66:67], v[66:67], v[98:99] op_sel_hi:[1,0]
	v_pk_mul_f32 v[68:69], v[68:69], v[98:99] op_sel_hi:[1,0]
	s_waitcnt vmcnt(5)
	v_pk_mul_f32 v[66:67], v[82:83], v[66:67]
	v_pk_mul_f32 v[68:69], v[84:85], v[68:69]
	s_waitcnt vmcnt(4)
	v_pk_fma_f32 v[66:67], v[78:79], v[66:67], v[86:87]
	v_pk_fma_f32 v[68:69], v[80:81], v[68:69], v[88:89]
	v_cvt_pk_bf16_f32 v66, v66, v67
	v_cvt_pk_bf16_f32 v67, v68, v69
	global_store_dwordx2 v[94:95], v[66:67], off offset:256
	global_load_dwordx4 v[66:69], v[24:25], off offset:1024
	s_nop 0
	global_load_dwordx4 v[78:81], v[96:97], off
	global_load_dwordx4 v[82:85], v[92:93], off offset:1024
	v_pk_mul_f32 v[70:71], v[70:71], v[98:99] op_sel_hi:[1,0]
	v_pk_mul_f32 v[72:73], v[72:73], v[98:99] op_sel_hi:[1,0]
	v_mov_b32_e32 v35, v23
	v_lshl_add_u64 v[86:87], v[90:91], 0, v[34:35]
	v_pk_mul_f32 v[74:75], v[74:75], v[98:99] op_sel_hi:[1,0]
	v_pk_mul_f32 v[76:77], v[76:77], v[98:99] op_sel_hi:[1,0]
	v_mov_b32_e32 v37, v23
	v_pk_mul_f32 v[16:17], v[16:17], v[98:99] op_sel_hi:[1,0]
	v_pk_mul_f32 v[18:19], v[18:19], v[98:99] op_sel_hi:[1,0]
	s_waitcnt vmcnt(2)
	v_pk_mul_f32 v[66:67], v[66:67], v[70:71]
	s_waitcnt vmcnt(1)
	v_pk_add_f32 v[70:71], v[78:79], 1.0 op_sel_hi:[1,0]
	v_pk_mul_f32 v[68:69], v[68:69], v[72:73]
	v_pk_add_f32 v[72:73], v[80:81], 1.0 op_sel_hi:[1,0]
	s_waitcnt vmcnt(0)
	v_pk_fma_f32 v[66:67], v[70:71], v[66:67], v[82:83]
	v_pk_fma_f32 v[68:69], v[72:73], v[68:69], v[84:85]
	v_cvt_pk_bf16_f32 v66, v66, v67
	v_cvt_pk_bf16_f32 v67, v68, v69
	global_store_dwordx2 v[94:95], v[66:67], off offset:768
	global_load_dwordx4 v[66:69], v[24:25], off offset:2048
	s_nop 0
	global_load_dwordx4 v[70:73], v[86:87], off
	global_load_dwordx4 v[78:81], v[92:93], off offset:2048
	v_lshl_add_u64 v[82:83], v[90:91], 0, v[36:37]
	s_waitcnt vmcnt(2)
	v_pk_mul_f32 v[66:67], v[66:67], v[74:75]
	s_waitcnt vmcnt(1)
	v_pk_add_f32 v[70:71], v[70:71], 1.0 op_sel_hi:[1,0]
	v_pk_mul_f32 v[68:69], v[68:69], v[76:77]
	v_pk_add_f32 v[72:73], v[72:73], 1.0 op_sel_hi:[1,0]
	s_waitcnt vmcnt(0)
	v_pk_fma_f32 v[66:67], v[70:71], v[66:67], v[78:79]
	v_pk_fma_f32 v[68:69], v[72:73], v[68:69], v[80:81]
	v_cvt_pk_bf16_f32 v66, v66, v67
	v_cvt_pk_bf16_f32 v67, v68, v69
	global_store_dwordx2 v[94:95], v[66:67], off offset:1280
	global_load_dwordx4 v[66:69], v[24:25], off offset:3072
	s_nop 0
	global_load_dwordx4 v[70:73], v[82:83], off
	global_load_dwordx4 v[74:77], v[92:93], off offset:3072
	s_waitcnt vmcnt(2)
	v_pk_mul_f32 v[16:17], v[66:67], v[16:17]
	s_waitcnt vmcnt(1)
	v_pk_add_f32 v[66:67], v[70:71], 1.0 op_sel_hi:[1,0]
	v_pk_mul_f32 v[18:19], v[68:69], v[18:19]
	v_pk_add_f32 v[68:69], v[72:73], 1.0 op_sel_hi:[1,0]
	s_waitcnt vmcnt(0)
	v_pk_fma_f32 v[16:17], v[66:67], v[16:17], v[74:75]
	v_pk_fma_f32 v[18:19], v[68:69], v[18:19], v[76:77]
	v_cvt_pk_bf16_f32 v16, v16, v17
	v_cvt_pk_bf16_f32 v17, v18, v19
	global_store_dwordx2 v[94:95], v[16:17], off offset:1792
	s_and_saveexec_b64 s[64:65], vcc
	s_cbranch_execz .LBB0_209
	v_add_u32_e32 v16, 0xffffe000, v44
	v_lshrrev_b32_e32 v16, 12, v16
	v_add_u32_e32 v16, 1, v16
	v_cmp_lt_i32_e32 vcc, s84, v44
	v_mul_f32_e32 v80, v13, v13
	v_fmac_f32_e32 v80, v12, v12
	v_cndmask_b32_e32 v18, 0, v16, vcc
	v_mov_b64_e32 v[16:17], s[14:15]
	v_mad_u64_u32 v[44:45], s[6:7], v18, s33, v[16:17]
	v_lshl_add_u64 v[74:75], v[44:45], 0, s[58:59]
	v_lshl_add_u64 v[66:67], v[74:75], 0, v[22:23]
	global_load_dwordx4 v[16:19], v[24:25], off
	v_lshl_add_u64 v[44:45], v[44:45], 0, v[22:23]
	global_load_dwordx4 v[66:69], v[66:67], off
	v_fmac_f32_e32 v80, v14, v14
	global_load_dwordx4 v[70:73], v[44:45], off
	v_fmac_f32_e32 v80, v15, v15
	v_fmac_f32_e32 v80, v8, v8
	v_fmac_f32_e32 v80, v9, v9
	v_fmac_f32_e32 v80, v10, v10
	v_fmac_f32_e32 v80, v11, v11
	v_fmac_f32_e32 v80, v4, v4
	v_fmac_f32_e32 v80, v5, v5
	v_fmac_f32_e32 v80, v6, v6
	v_pk_mul_f32 v[78:79], v[0:1], v[0:1]
	v_fmac_f32_e32 v80, v7, v7
	v_add_f32_e32 v78, v78, v80
	v_pk_mul_f32 v[76:77], v[2:3], v[2:3]
	v_add_f32_e32 v78, v79, v78
	v_add_f32_e32 v76, v76, v78
	v_add_f32_e32 v76, v77, v76
	v_mov_b32_e32 v78, v76
	s_nop 1
	v_add_f32_dpp v78, v78, v78 quad_perm:[1,0,3,2] row_mask:0xf bank_mask:0xf bound_ctrl:1
	s_nop 1
	v_add_f32_dpp v78, v78, v78 quad_perm:[2,3,0,1] row_mask:0xf bank_mask:0xf bound_ctrl:1
	s_nop 1
	v_add_f32_dpp v78, v78, v78 row_half_mirror row_mask:0xf bank_mask:0xf bound_ctrl:1
	s_nop 1
	v_add_f32_dpp v78, v78, v78 row_mirror row_mask:0xf bank_mask:0xf bound_ctrl:1
	v_mov_b32_e32 v77, v78
	s_nop 1
	v_permlane16_swap_b32_e32 v77, v78
	s_nop 1
	v_add_f32_e32 v78, v77, v78
	v_mov_b32_e32 v77, v78
	s_nop 1
	v_permlane32_swap_b32_e32 v77, v78
	s_nop 1
	v_add_f32_e32 v78, v77, v78
	v_lshl_add_u64 v[76:77], v[38:39], 0, v[26:27]
	v_add_co_u32_e64 v76, s[6:7], s83, v76
	v_fmamk_f32 v78, v78, 0x3a800000, v46
	v_mul_f32_e32 v79, 0x4b800000, v78
	v_cmp_gt_f32_e32 vcc, s82, v78
	v_addc_co_u32_e64 v77, s[6:7], 0, v77, s[6:7]
	s_nop 0
	v_cndmask_b32_e32 v78, v78, v79, vcc
	v_rsq_f32_e32 v80, v78
	v_lshl_add_u64 v[78:79], v[74:75], 0, v[32:33]
	v_mul_f32_e32 v33, 0x45800000, v80
	v_cndmask_b32_e32 v80, v80, v33, vcc
	v_pk_mul_f32 v[12:13], v[12:13], v[80:81] op_sel_hi:[1,0]
	v_pk_mul_f32 v[14:15], v[14:15], v[80:81] op_sel_hi:[1,0]
	v_pk_mul_f32 v[8:9], v[8:9], v[80:81] op_sel_hi:[1,0]
	v_pk_mul_f32 v[10:11], v[10:11], v[80:81] op_sel_hi:[1,0]
	v_pk_mul_f32 v[4:5], v[4:5], v[80:81] op_sel_hi:[1,0]
	v_pk_mul_f32 v[6:7], v[6:7], v[80:81] op_sel_hi:[1,0]
	v_pk_mul_f32 v[0:1], v[0:1], v[80:81] op_sel_hi:[1,0]
	v_pk_mul_f32 v[2:3], v[2:3], v[80:81] op_sel_hi:[1,0]
	s_waitcnt vmcnt(2)
	v_pk_mul_f32 v[12:13], v[16:17], v[12:13]
	v_pk_mul_f32 v[14:15], v[18:19], v[14:15]
	s_waitcnt vmcnt(1)
	v_pk_add_f32 v[16:17], v[66:67], 1.0 op_sel_hi:[1,0]
	v_pk_add_f32 v[18:19], v[68:69], 1.0 op_sel_hi:[1,0]
	s_waitcnt vmcnt(0)
	v_pk_fma_f32 v[12:13], v[16:17], v[12:13], v[70:71]
	v_pk_fma_f32 v[14:15], v[18:19], v[14:15], v[72:73]
	v_cvt_pk_bf16_f32 v12, v12, v13
	v_cvt_pk_bf16_f32 v13, v14, v15
	global_store_dwordx2 v[76:77], v[12:13], off offset:256
	global_load_dwordx4 v[12:15], v[24:25], off offset:1024
	s_nop 0
	global_load_dwordx4 v[16:19], v[78:79], off
	global_load_dwordx4 v[66:69], v[44:45], off offset:1024
	v_lshl_add_u64 v[70:71], v[74:75], 0, v[34:35]
	s_waitcnt vmcnt(2)
	v_pk_mul_f32 v[8:9], v[12:13], v[8:9]
	s_waitcnt vmcnt(1)
	v_pk_add_f32 v[12:13], v[16:17], 1.0 op_sel_hi:[1,0]
	v_pk_mul_f32 v[10:11], v[14:15], v[10:11]
	v_pk_add_f32 v[14:15], v[18:19], 1.0 op_sel_hi:[1,0]
	s_waitcnt vmcnt(0)
	v_pk_fma_f32 v[8:9], v[12:13], v[8:9], v[66:67]
	v_pk_fma_f32 v[10:11], v[14:15], v[10:11], v[68:69]
	v_cvt_pk_bf16_f32 v8, v8, v9
	v_cvt_pk_bf16_f32 v9, v10, v11
	global_store_dwordx2 v[76:77], v[8:9], off offset:768
	global_load_dwordx4 v[8:11], v[24:25], off offset:2048
	s_nop 0
	global_load_dwordx4 v[12:15], v[70:71], off
	global_load_dwordx4 v[16:19], v[44:45], off offset:2048
	v_lshl_add_u64 v[66:67], v[74:75], 0, v[36:37]
	s_waitcnt vmcnt(2)
	v_pk_mul_f32 v[4:5], v[4:5], v[8:9]
	s_waitcnt vmcnt(1)
	v_pk_add_f32 v[8:9], v[12:13], 1.0 op_sel_hi:[1,0]
	v_pk_mul_f32 v[6:7], v[6:7], v[10:11]
	v_pk_add_f32 v[10:11], v[14:15], 1.0 op_sel_hi:[1,0]
	s_waitcnt vmcnt(0)
	v_pk_fma_f32 v[4:5], v[4:5], v[8:9], v[16:17]
	v_pk_fma_f32 v[6:7], v[6:7], v[10:11], v[18:19]
	v_cvt_pk_bf16_f32 v4, v4, v5
	v_cvt_pk_bf16_f32 v5, v6, v7
	global_store_dwordx2 v[76:77], v[4:5], off offset:1280
	global_load_dwordx4 v[4:7], v[24:25], off offset:3072
	s_nop 0
	global_load_dwordx4 v[8:11], v[66:67], off
	global_load_dwordx4 v[12:15], v[44:45], off offset:3072
	s_waitcnt vmcnt(2)
	v_pk_mul_f32 v[0:1], v[0:1], v[4:5]
	s_waitcnt vmcnt(1)
	v_pk_add_f32 v[4:5], v[8:9], 1.0 op_sel_hi:[1,0]
	v_pk_mul_f32 v[2:3], v[2:3], v[6:7]
	v_pk_add_f32 v[6:7], v[10:11], 1.0 op_sel_hi:[1,0]
	s_waitcnt vmcnt(0)
	v_pk_fma_f32 v[0:1], v[0:1], v[4:5], v[12:13]
	v_pk_fma_f32 v[2:3], v[2:3], v[6:7], v[14:15]
	v_cvt_pk_bf16_f32 v0, v0, v1
	v_cvt_pk_bf16_f32 v1, v2, v3
	global_store_dwordx2 v[76:77], v[0:1], off offset:1792
	s_branch .LBB0_209

.LBB0_717:
	global_load_dwordx4 v[70:73], v[42:43], off offset:-3072
	global_load_dwordx4 v[16:19], v[42:43], off
	global_load_dwordx4 v[74:77], v[42:43], off offset:-2048
	global_load_dwordx4 v[78:81], v[42:43], off offset:-1024
	v_add_u32_e32 v2, 0xffffe000, v67
	v_lshrrev_b32_e32 v2, 12, v2
	v_add_u32_e32 v2, 1, v2
	v_cmp_lt_i32_e32 vcc, s84, v67
	v_mov_b64_e32 v[0:1], s[14:15]
	v_add_u32_e32 v68, s80, v67
	v_cndmask_b32_e32 v2, 0, v2, vcc
	v_mad_u64_u32 v[0:1], s[6:7], v2, s81, v[0:1]
	v_lshl_add_u64 v[94:95], v[0:1], 0, s[10:11]
	v_lshl_add_u64 v[2:3], v[94:95], 0, v[22:23]
	v_lshl_add_u64 v[96:97], v[0:1], 0, s[58:59]
	global_load_dwordx4 v[82:85], v[2:3], off
	global_load_dwordx4 v[86:89], v[26:27], off
	v_lshl_add_u64 v[0:1], v[96:97], 0, v[22:23]
	global_load_dwordx4 v[90:93], v[0:1], off
	v_cmp_gt_i32_e32 vcc, s81, v68
	v_mov_b32_e32 v37, v23
	v_lshl_add_u64 v[100:101], v[94:95], 0, v[36:37]
	s_waitcnt vmcnt(6)
	v_mul_f32_e32 v4, v71, v71
	v_fmac_f32_e32 v4, v70, v70
	v_fmac_f32_e32 v4, v72, v72
	v_fmac_f32_e32 v4, v73, v73
	s_waitcnt vmcnt(4)
	v_fmac_f32_e32 v4, v74, v74
	v_fmac_f32_e32 v4, v75, v75
	v_fmac_f32_e32 v4, v76, v76
	v_fmac_f32_e32 v4, v77, v77
	s_waitcnt vmcnt(3)
	v_fmac_f32_e32 v4, v78, v78
	v_fmac_f32_e32 v4, v79, v79
	v_fmac_f32_e32 v4, v80, v80
	v_pk_mul_f32 v[2:3], v[16:17], v[16:17]
	v_fmac_f32_e32 v4, v81, v81
	v_add_f32_e32 v2, v2, v4
	v_pk_mul_f32 v[0:1], v[18:19], v[18:19]
	v_add_f32_e32 v2, v3, v2
	v_add_f32_e32 v0, v0, v2
	v_add_f32_e32 v0, v1, v0
	v_mov_b32_e32 v39, v0
	s_nop 1
	v_add_f32_dpp v39, v39, v39 quad_perm:[1,0,3,2] row_mask:0xf bank_mask:0xf bound_ctrl:1
	s_nop 1
	v_add_f32_dpp v39, v39, v39 quad_perm:[2,3,0,1] row_mask:0xf bank_mask:0xf bound_ctrl:1
	s_nop 1
	v_add_f32_dpp v39, v39, v39 row_half_mirror row_mask:0xf bank_mask:0xf bound_ctrl:1
	s_nop 1
	v_add_f32_dpp v39, v39, v39 row_mirror row_mask:0xf bank_mask:0xf bound_ctrl:1
	v_mov_b32_e32 v1, v39
	s_nop 1
	v_permlane16_swap_b32_e32 v1, v39
	s_nop 1
	v_add_f32_e32 v39, v1, v39
	v_mov_b32_e32 v1, v39
	s_nop 1
	v_permlane32_swap_b32_e32 v1, v39
	s_nop 1
	v_add_f32_e32 v39, v1, v39
	v_cndmask_b32_e32 v2, v67, v68, vcc
	s_waitcnt vmcnt(2)
	v_pk_add_f32 v[82:83], v[82:83], 1.0 op_sel_hi:[1,0]
	v_pk_add_f32 v[84:85], v[84:85], 1.0 op_sel_hi:[1,0]
	v_lshl_add_u64 v[0:1], v[46:47], 0, v[28:29]
	v_add_co_u32_e64 v98, s[6:7], s86, v0
	v_addc_co_u32_e64 v99, s[6:7], 0, v1, s[6:7]
	v_ashrrev_i32_e32 v3, 31, v2
	v_lshlrev_b64 v[0:1], 12, v[2:3]
	v_lshl_add_u64 v[0:1], v[24:25], 0, v[0:1]
	global_load_dwordx4 v[12:15], v[0:1], off
	global_load_dwordx4 v[8:11], v[0:1], off offset:1024
	global_load_dwordx4 v[4:7], v[0:1], off offset:2048
	s_nop 0
	global_load_dwordx4 v[0:3], v[0:1], off offset:3072
	v_fmamk_f32 v39, v39, 0x3a800000, v21
	v_mul_f32_e32 v41, 0x4b800000, v39
	v_cmp_gt_f32_e64 s[6:7], s85, v39
	s_nop 1
	v_cndmask_b32_e64 v39, v39, v41, s[6:7]
	v_rsq_f32_e32 v39, v39
	s_nop 0
	v_mul_f32_e32 v41, 0x45800000, v39
	v_cndmask_b32_e64 v102, v39, v41, s[6:7]
	v_pk_mul_f32 v[70:71], v[70:71], v[102:103] op_sel_hi:[1,0]
	v_pk_mul_f32 v[72:73], v[72:73], v[102:103] op_sel_hi:[1,0]
	s_waitcnt vmcnt(5)
	v_pk_mul_f32 v[70:71], v[86:87], v[70:71]
	v_pk_mul_f32 v[72:73], v[88:89], v[72:73]
	s_waitcnt vmcnt(4)
	v_pk_fma_f32 v[70:71], v[82:83], v[70:71], v[90:91]
	v_pk_fma_f32 v[72:73], v[84:85], v[72:73], v[92:93]
	v_cvt_pk_bf16_f32 v70, v70, v71
	v_cvt_pk_bf16_f32 v71, v72, v73
	global_store_dwordx2 v[98:99], v[70:71], off offset:256
	global_load_dwordx4 v[70:73], v[26:27], off offset:1024
	s_nop 0
	global_load_dwordx4 v[82:85], v[100:101], off
	v_lshl_add_u64 v[86:87], v[96:97], 0, v[36:37]
	global_load_dwordx4 v[86:89], v[86:87], off
	v_pk_mul_f32 v[74:75], v[74:75], v[102:103] op_sel_hi:[1,0]
	v_pk_mul_f32 v[76:77], v[76:77], v[102:103] op_sel_hi:[1,0]
	v_mov_b32_e32 v39, v23
	v_lshl_add_u64 v[90:91], v[94:95], 0, v[38:39]
	v_pk_mul_f32 v[78:79], v[78:79], v[102:103] op_sel_hi:[1,0]
	v_pk_mul_f32 v[80:81], v[80:81], v[102:103] op_sel_hi:[1,0]
	v_mov_b32_e32 v41, v23
	v_pk_mul_f32 v[16:17], v[16:17], v[102:103] op_sel_hi:[1,0]
	v_pk_mul_f32 v[18:19], v[18:19], v[102:103] op_sel_hi:[1,0]
	s_waitcnt vmcnt(2)
	v_pk_mul_f32 v[70:71], v[70:71], v[74:75]
	s_waitcnt vmcnt(1)
	v_pk_add_f32 v[74:75], v[82:83], 1.0 op_sel_hi:[1,0]
	v_pk_mul_f32 v[72:73], v[72:73], v[76:77]
	v_pk_add_f32 v[76:77], v[84:85], 1.0 op_sel_hi:[1,0]
	s_waitcnt vmcnt(0)
	v_pk_fma_f32 v[70:71], v[74:75], v[70:71], v[86:87]
	v_pk_fma_f32 v[72:73], v[76:77], v[72:73], v[88:89]
	v_cvt_pk_bf16_f32 v70, v70, v71
	v_cvt_pk_bf16_f32 v71, v72, v73
	global_store_dwordx2 v[98:99], v[70:71], off offset:768
	global_load_dwordx4 v[70:73], v[26:27], off offset:2048
	s_nop 0
	global_load_dwordx4 v[74:77], v[90:91], off
	v_lshl_add_u64 v[82:83], v[96:97], 0, v[38:39]
	global_load_dwordx4 v[82:85], v[82:83], off
	v_lshl_add_u64 v[86:87], v[94:95], 0, v[40:41]
	s_waitcnt vmcnt(2)
	v_pk_mul_f32 v[70:71], v[70:71], v[78:79]
	s_waitcnt vmcnt(1)
	v_pk_add_f32 v[74:75], v[74:75], 1.0 op_sel_hi:[1,0]
	v_pk_mul_f32 v[72:73], v[72:73], v[80:81]
	v_pk_add_f32 v[76:77], v[76:77], 1.0 op_sel_hi:[1,0]
	s_waitcnt vmcnt(0)
	v_pk_fma_f32 v[70:71], v[74:75], v[70:71], v[82:83]
	v_pk_fma_f32 v[72:73], v[76:77], v[72:73], v[84:85]
	v_cvt_pk_bf16_f32 v70, v70, v71
	v_cvt_pk_bf16_f32 v71, v72, v73
	global_store_dwordx2 v[98:99], v[70:71], off offset:1280
	global_load_dwordx4 v[70:73], v[26:27], off offset:3072
	s_nop 0
	global_load_dwordx4 v[74:77], v[86:87], off
	v_lshl_add_u64 v[78:79], v[96:97], 0, v[40:41]
	global_load_dwordx4 v[78:81], v[78:79], off
	s_waitcnt vmcnt(2)
	v_pk_mul_f32 v[16:17], v[70:71], v[16:17]
	s_waitcnt vmcnt(1)
	v_pk_add_f32 v[70:71], v[74:75], 1.0 op_sel_hi:[1,0]
	v_pk_mul_f32 v[18:19], v[72:73], v[18:19]
	v_pk_add_f32 v[72:73], v[76:77], 1.0 op_sel_hi:[1,0]
	s_waitcnt vmcnt(0)
	v_pk_fma_f32 v[16:17], v[70:71], v[16:17], v[78:79]
	v_pk_fma_f32 v[18:19], v[72:73], v[18:19], v[80:81]
	v_cvt_pk_bf16_f32 v16, v16, v17
	v_cvt_pk_bf16_f32 v17, v18, v19
	global_store_dwordx2 v[98:99], v[16:17], off offset:1792
	s_and_saveexec_b64 s[64:65], vcc
	s_cbranch_execz .LBB0_716
	v_add_u32_e32 v16, 0xffffe000, v68
	v_lshrrev_b32_e32 v16, 12, v16
	v_add_u32_e32 v16, 1, v16
	v_cmp_lt_i32_e32 vcc, s84, v68
	v_mul_f32_e32 v84, v13, v13
	v_fmac_f32_e32 v84, v12, v12
	v_cndmask_b32_e32 v18, 0, v16, vcc
	v_mov_b64_e32 v[16:17], s[14:15]
	v_mad_u64_u32 v[16:17], s[6:7], v18, s81, v[16:17]
	v_lshl_add_u64 v[76:77], v[16:17], 0, s[10:11]
	v_lshl_add_u64 v[78:79], v[16:17], 0, s[58:59]
	v_lshl_add_u64 v[68:69], v[76:77], 0, v[22:23]
	global_load_dwordx4 v[16:19], v[26:27], off
	v_lshl_add_u64 v[72:73], v[78:79], 0, v[22:23]
	global_load_dwordx4 v[68:71], v[68:69], off
	v_fmac_f32_e32 v84, v14, v14
	global_load_dwordx4 v[72:75], v[72:73], off
	v_fmac_f32_e32 v84, v15, v15
	v_fmac_f32_e32 v84, v8, v8
	v_fmac_f32_e32 v84, v9, v9
	v_fmac_f32_e32 v84, v10, v10
	v_fmac_f32_e32 v84, v11, v11
	v_fmac_f32_e32 v84, v4, v4
	v_fmac_f32_e32 v84, v5, v5
	v_fmac_f32_e32 v84, v6, v6
	v_pk_mul_f32 v[82:83], v[0:1], v[0:1]
	v_fmac_f32_e32 v84, v7, v7
	v_add_f32_e32 v82, v82, v84
	v_pk_mul_f32 v[80:81], v[2:3], v[2:3]
	v_add_f32_e32 v82, v83, v82
	v_add_f32_e32 v80, v80, v82
	v_add_f32_e32 v80, v81, v80
	v_mov_b32_e32 v82, v80
	s_nop 1
	v_add_f32_dpp v82, v82, v82 quad_perm:[1,0,3,2] row_mask:0xf bank_mask:0xf bound_ctrl:1
	s_nop 1
	v_add_f32_dpp v82, v82, v82 quad_perm:[2,3,0,1] row_mask:0xf bank_mask:0xf bound_ctrl:1
	s_nop 1
	v_add_f32_dpp v82, v82, v82 row_half_mirror row_mask:0xf bank_mask:0xf bound_ctrl:1
	s_nop 1
	v_add_f32_dpp v82, v82, v82 row_mirror row_mask:0xf bank_mask:0xf bound_ctrl:1
	v_mov_b32_e32 v81, v82
	s_nop 1
	v_permlane16_swap_b32_e32 v81, v82
	s_nop 1
	v_add_f32_e32 v82, v81, v82
	v_mov_b32_e32 v81, v82
	s_nop 1
	v_permlane32_swap_b32_e32 v81, v82
	s_nop 1
	v_add_f32_e32 v82, v81, v82
	v_lshl_add_u64 v[80:81], v[44:45], 0, v[28:29]
	v_add_co_u32_e64 v80, s[6:7], s86, v80
	v_fmamk_f32 v82, v82, 0x3a800000, v21
	v_mul_f32_e32 v83, 0x4b800000, v82
	v_cmp_gt_f32_e32 vcc, s85, v82
	v_addc_co_u32_e64 v81, s[6:7], 0, v81, s[6:7]
	s_nop 0
	v_cndmask_b32_e32 v82, v82, v83, vcc
	v_rsq_f32_e32 v84, v82
	v_lshl_add_u64 v[82:83], v[76:77], 0, v[36:37]
	v_mul_f32_e32 v85, 0x45800000, v84
	v_cndmask_b32_e32 v84, v84, v85, vcc
	v_pk_mul_f32 v[12:13], v[12:13], v[84:85] op_sel_hi:[1,0]
	v_pk_mul_f32 v[14:15], v[14:15], v[84:85] op_sel_hi:[1,0]
	v_pk_mul_f32 v[8:9], v[8:9], v[84:85] op_sel_hi:[1,0]
	v_pk_mul_f32 v[10:11], v[10:11], v[84:85] op_sel_hi:[1,0]
	v_pk_mul_f32 v[4:5], v[4:5], v[84:85] op_sel_hi:[1,0]
	v_pk_mul_f32 v[6:7], v[6:7], v[84:85] op_sel_hi:[1,0]
	v_pk_mul_f32 v[0:1], v[0:1], v[84:85] op_sel_hi:[1,0]
	v_pk_mul_f32 v[2:3], v[2:3], v[84:85] op_sel_hi:[1,0]
	s_waitcnt vmcnt(2)
	v_pk_mul_f32 v[12:13], v[16:17], v[12:13]
	v_pk_mul_f32 v[14:15], v[18:19], v[14:15]
	s_waitcnt vmcnt(1)
	v_pk_add_f32 v[16:17], v[68:69], 1.0 op_sel_hi:[1,0]
	v_pk_add_f32 v[18:19], v[70:71], 1.0 op_sel_hi:[1,0]
	s_waitcnt vmcnt(0)
	v_pk_fma_f32 v[12:13], v[16:17], v[12:13], v[72:73]
	v_pk_fma_f32 v[14:15], v[18:19], v[14:15], v[74:75]
	v_cvt_pk_bf16_f32 v12, v12, v13
	v_cvt_pk_bf16_f32 v13, v14, v15
	global_store_dwordx2 v[80:81], v[12:13], off offset:256
	global_load_dwordx4 v[12:15], v[26:27], off offset:1024
	s_nop 0
	global_load_dwordx4 v[16:19], v[82:83], off
	v_lshl_add_u64 v[68:69], v[78:79], 0, v[36:37]
	global_load_dwordx4 v[68:71], v[68:69], off
	v_lshl_add_u64 v[72:73], v[76:77], 0, v[38:39]
	s_waitcnt vmcnt(2)
	v_pk_mul_f32 v[8:9], v[12:13], v[8:9]
	s_waitcnt vmcnt(1)
	v_pk_add_f32 v[12:13], v[16:17], 1.0 op_sel_hi:[1,0]
	v_pk_mul_f32 v[10:11], v[14:15], v[10:11]
	v_pk_add_f32 v[14:15], v[18:19], 1.0 op_sel_hi:[1,0]
	s_waitcnt vmcnt(0)
	v_pk_fma_f32 v[8:9], v[12:13], v[8:9], v[68:69]
	v_pk_fma_f32 v[10:11], v[14:15], v[10:11], v[70:71]
	v_cvt_pk_bf16_f32 v8, v8, v9
	v_cvt_pk_bf16_f32 v9, v10, v11
	global_store_dwordx2 v[80:81], v[8:9], off offset:768
	global_load_dwordx4 v[8:11], v[26:27], off offset:2048
	s_nop 0
	global_load_dwordx4 v[12:15], v[72:73], off
	v_lshl_add_u64 v[16:17], v[78:79], 0, v[38:39]
	global_load_dwordx4 v[16:19], v[16:17], off
	v_lshl_add_u64 v[68:69], v[76:77], 0, v[40:41]
	s_waitcnt vmcnt(2)
	v_pk_mul_f32 v[4:5], v[4:5], v[8:9]
	s_waitcnt vmcnt(1)
	v_pk_add_f32 v[8:9], v[12:13], 1.0 op_sel_hi:[1,0]
	v_pk_mul_f32 v[6:7], v[6:7], v[10:11]
	v_pk_add_f32 v[10:11], v[14:15], 1.0 op_sel_hi:[1,0]
	s_waitcnt vmcnt(0)
	v_pk_fma_f32 v[4:5], v[4:5], v[8:9], v[16:17]
	v_pk_fma_f32 v[6:7], v[6:7], v[10:11], v[18:19]
	v_cvt_pk_bf16_f32 v4, v4, v5
	v_cvt_pk_bf16_f32 v5, v6, v7
	global_store_dwordx2 v[80:81], v[4:5], off offset:1280
	global_load_dwordx4 v[4:7], v[26:27], off offset:3072
	s_nop 0
	global_load_dwordx4 v[8:11], v[68:69], off
	v_lshl_add_u64 v[12:13], v[78:79], 0, v[40:41]
	global_load_dwordx4 v[12:15], v[12:13], off
	s_waitcnt vmcnt(2)
	v_pk_mul_f32 v[0:1], v[0:1], v[4:5]
	s_waitcnt vmcnt(1)
	v_pk_add_f32 v[4:5], v[8:9], 1.0 op_sel_hi:[1,0]
	v_pk_mul_f32 v[2:3], v[2:3], v[6:7]
	v_pk_add_f32 v[6:7], v[10:11], 1.0 op_sel_hi:[1,0]
	s_waitcnt vmcnt(0)
	v_pk_fma_f32 v[0:1], v[0:1], v[4:5], v[12:13]
	v_pk_fma_f32 v[2:3], v[2:3], v[6:7], v[14:15]
	v_cvt_pk_bf16_f32 v0, v0, v1
	v_cvt_pk_bf16_f32 v1, v2, v3
	global_store_dwordx2 v[80:81], v[0:1], off offset:1792
	s_branch .LBB0_716

.LBB0_1206:
	global_load_dwordx4 v[76:79], v[48:49], off offset:-3072
	global_load_dwordx4 v[16:19], v[48:49], off
	global_load_dwordx4 v[80:83], v[48:49], off offset:-2048
	global_load_dwordx4 v[84:87], v[48:49], off offset:-1024
	v_add_u32_e32 v2, 0xffffe000, v73
	v_lshrrev_b32_e32 v2, 12, v2
	v_add_u32_e32 v2, 6, v2
	v_cmp_lt_i32_e32 vcc, s83, v73
	v_mov_b64_e32 v[0:1], s[4:5]
	v_add_u32_e32 v74, s78, v73
	v_cndmask_b32_e32 v2, 5, v2, vcc
	v_mad_u64_u32 v[0:1], s[8:9], v2, s79, v[0:1]
	v_lshl_add_u64 v[100:101], v[0:1], 0, s[54:55]
	v_lshl_add_u64 v[2:3], v[100:101], 0, v[22:23]
	v_lshl_add_u64 v[102:103], v[0:1], 0, s[56:57]
	global_load_dwordx4 v[88:91], v[2:3], off
	global_load_dwordx4 v[92:95], v[26:27], off
	v_lshl_add_u64 v[0:1], v[102:103], 0, v[22:23]
	global_load_dwordx4 v[96:99], v[0:1], off
	v_cmp_gt_i32_e32 vcc, s79, v74
	v_mov_b32_e32 v43, v23
	v_lshl_add_u64 v[106:107], v[100:101], 0, v[42:43]
	s_waitcnt vmcnt(6)
	v_mul_f32_e32 v4, v77, v77
	v_fmac_f32_e32 v4, v76, v76
	v_fmac_f32_e32 v4, v78, v78
	v_fmac_f32_e32 v4, v79, v79
	s_waitcnt vmcnt(4)
	v_fmac_f32_e32 v4, v80, v80
	v_fmac_f32_e32 v4, v81, v81
	v_fmac_f32_e32 v4, v82, v82
	v_fmac_f32_e32 v4, v83, v83
	s_waitcnt vmcnt(3)
	v_fmac_f32_e32 v4, v84, v84
	v_fmac_f32_e32 v4, v85, v85
	v_fmac_f32_e32 v4, v86, v86
	v_pk_mul_f32 v[2:3], v[16:17], v[16:17]
	v_fmac_f32_e32 v4, v87, v87
	v_add_f32_e32 v2, v2, v4
	v_pk_mul_f32 v[0:1], v[18:19], v[18:19]
	v_add_f32_e32 v2, v3, v2
	v_add_f32_e32 v0, v0, v2
	v_add_f32_e32 v0, v1, v0
	v_mov_b32_e32 v45, v0
	s_nop 1
	v_add_f32_dpp v45, v45, v45 quad_perm:[1,0,3,2] row_mask:0xf bank_mask:0xf bound_ctrl:1
	s_nop 1
	v_add_f32_dpp v45, v45, v45 quad_perm:[2,3,0,1] row_mask:0xf bank_mask:0xf bound_ctrl:1
	s_nop 1
	v_add_f32_dpp v45, v45, v45 row_half_mirror row_mask:0xf bank_mask:0xf bound_ctrl:1
	s_nop 1
	v_add_f32_dpp v45, v45, v45 row_mirror row_mask:0xf bank_mask:0xf bound_ctrl:1
	v_mov_b32_e32 v1, v45
	s_nop 1
	v_permlane16_swap_b32_e32 v1, v45
	s_nop 1
	v_add_f32_e32 v45, v1, v45
	v_mov_b32_e32 v1, v45
	s_nop 1
	v_permlane32_swap_b32_e32 v1, v45
	s_nop 1
	v_add_f32_e32 v45, v1, v45
	v_cndmask_b32_e32 v2, v73, v74, vcc
	s_waitcnt vmcnt(2)
	v_pk_add_f32 v[88:89], v[88:89], 1.0 op_sel_hi:[1,0]
	v_pk_add_f32 v[90:91], v[90:91], 1.0 op_sel_hi:[1,0]
	v_lshl_add_u64 v[0:1], v[52:53], 0, v[34:35]
	v_add_co_u32_e64 v104, s[8:9], s84, v0
	v_addc_co_u32_e64 v105, s[8:9], 0, v1, s[8:9]
	v_ashrrev_i32_e32 v3, 31, v2
	v_lshlrev_b64 v[0:1], 12, v[2:3]
	v_lshl_add_u64 v[0:1], v[24:25], 0, v[0:1]
	global_load_dwordx4 v[12:15], v[0:1], off
	global_load_dwordx4 v[8:11], v[0:1], off offset:1024
	global_load_dwordx4 v[4:7], v[0:1], off offset:2048
	s_nop 0
	global_load_dwordx4 v[0:3], v[0:1], off offset:3072
	v_fmamk_f32 v45, v45, 0x3a800000, v21
	v_mul_f32_e32 v47, 0x4b800000, v45
	v_cmp_gt_f32_e64 s[8:9], s82, v45
	s_nop 1
	v_cndmask_b32_e64 v45, v45, v47, s[8:9]
	v_rsq_f32_e32 v45, v45
	s_nop 0
	v_mul_f32_e32 v47, 0x45800000, v45
	v_cndmask_b32_e64 v108, v45, v47, s[8:9]
	v_pk_mul_f32 v[76:77], v[76:77], v[108:109] op_sel_hi:[1,0]
	v_pk_mul_f32 v[78:79], v[78:79], v[108:109] op_sel_hi:[1,0]
	s_waitcnt vmcnt(5)
	v_pk_mul_f32 v[76:77], v[92:93], v[76:77]
	v_pk_mul_f32 v[78:79], v[94:95], v[78:79]
	s_waitcnt vmcnt(4)
	v_pk_fma_f32 v[76:77], v[88:89], v[76:77], v[96:97]
	v_pk_fma_f32 v[78:79], v[90:91], v[78:79], v[98:99]
	v_cvt_pk_bf16_f32 v76, v76, v77
	v_cvt_pk_bf16_f32 v77, v78, v79
	global_store_dwordx2 v[104:105], v[76:77], off offset:256
	global_load_dwordx4 v[76:79], v[28:29], off
	s_nop 0
	global_load_dwordx4 v[88:91], v[106:107], off
	v_lshl_add_u64 v[92:93], v[102:103], 0, v[42:43]
	global_load_dwordx4 v[92:95], v[92:93], off
	v_pk_mul_f32 v[80:81], v[80:81], v[108:109] op_sel_hi:[1,0]
	v_pk_mul_f32 v[82:83], v[82:83], v[108:109] op_sel_hi:[1,0]
	v_mov_b32_e32 v45, v23
	v_lshl_add_u64 v[96:97], v[100:101], 0, v[44:45]
	v_pk_mul_f32 v[84:85], v[84:85], v[108:109] op_sel_hi:[1,0]
	v_pk_mul_f32 v[86:87], v[86:87], v[108:109] op_sel_hi:[1,0]
	v_mov_b32_e32 v47, v23
	v_pk_mul_f32 v[16:17], v[16:17], v[108:109] op_sel_hi:[1,0]
	v_pk_mul_f32 v[18:19], v[18:19], v[108:109] op_sel_hi:[1,0]
	s_waitcnt vmcnt(2)
	v_pk_mul_f32 v[76:77], v[76:77], v[80:81]
	s_waitcnt vmcnt(1)
	v_pk_add_f32 v[80:81], v[88:89], 1.0 op_sel_hi:[1,0]
	v_pk_mul_f32 v[78:79], v[78:79], v[82:83]
	v_pk_add_f32 v[82:83], v[90:91], 1.0 op_sel_hi:[1,0]
	s_waitcnt vmcnt(0)
	v_pk_fma_f32 v[76:77], v[80:81], v[76:77], v[92:93]
	v_pk_fma_f32 v[78:79], v[82:83], v[78:79], v[94:95]
	v_cvt_pk_bf16_f32 v76, v76, v77
	v_cvt_pk_bf16_f32 v77, v78, v79
	global_store_dwordx2 v[104:105], v[76:77], off offset:768
	global_load_dwordx4 v[76:79], v[30:31], off
	s_nop 0
	global_load_dwordx4 v[80:83], v[96:97], off
	v_lshl_add_u64 v[88:89], v[102:103], 0, v[44:45]
	global_load_dwordx4 v[88:91], v[88:89], off
	v_lshl_add_u64 v[92:93], v[100:101], 0, v[46:47]
	s_waitcnt vmcnt(2)
	v_pk_mul_f32 v[76:77], v[76:77], v[84:85]
	s_waitcnt vmcnt(1)
	v_pk_add_f32 v[80:81], v[80:81], 1.0 op_sel_hi:[1,0]
	v_pk_mul_f32 v[78:79], v[78:79], v[86:87]
	v_pk_add_f32 v[82:83], v[82:83], 1.0 op_sel_hi:[1,0]
	s_waitcnt vmcnt(0)
	v_pk_fma_f32 v[76:77], v[80:81], v[76:77], v[88:89]
	v_pk_fma_f32 v[78:79], v[82:83], v[78:79], v[90:91]
	v_cvt_pk_bf16_f32 v76, v76, v77
	v_cvt_pk_bf16_f32 v77, v78, v79
	global_store_dwordx2 v[104:105], v[76:77], off offset:1280
	global_load_dwordx4 v[76:79], v[32:33], off
	s_nop 0
	global_load_dwordx4 v[80:83], v[92:93], off
	v_lshl_add_u64 v[84:85], v[102:103], 0, v[46:47]
	global_load_dwordx4 v[84:87], v[84:85], off
	s_waitcnt vmcnt(2)
	v_pk_mul_f32 v[16:17], v[76:77], v[16:17]
	s_waitcnt vmcnt(1)
	v_pk_add_f32 v[76:77], v[80:81], 1.0 op_sel_hi:[1,0]
	v_pk_mul_f32 v[18:19], v[78:79], v[18:19]
	v_pk_add_f32 v[78:79], v[82:83], 1.0 op_sel_hi:[1,0]
	s_waitcnt vmcnt(0)
	v_pk_fma_f32 v[16:17], v[76:77], v[16:17], v[84:85]
	v_pk_fma_f32 v[18:19], v[78:79], v[18:19], v[86:87]
	v_cvt_pk_bf16_f32 v16, v16, v17
	v_cvt_pk_bf16_f32 v17, v18, v19
	global_store_dwordx2 v[104:105], v[16:17], off offset:1792
	s_and_saveexec_b64 s[62:63], vcc
	s_cbranch_execz .LBB0_1205
	v_add_u32_e32 v16, 0xffffe000, v74
	v_lshrrev_b32_e32 v16, 12, v16
	v_add_u32_e32 v16, 6, v16
	v_cmp_lt_i32_e32 vcc, s83, v74
	v_mul_f32_e32 v90, v13, v13
	v_fmac_f32_e32 v90, v12, v12
	v_cndmask_b32_e32 v18, 5, v16, vcc
	v_mov_b64_e32 v[16:17], s[4:5]
	v_mad_u64_u32 v[16:17], s[8:9], v18, s79, v[16:17]
	v_lshl_add_u64 v[82:83], v[16:17], 0, s[54:55]
	v_lshl_add_u64 v[84:85], v[16:17], 0, s[56:57]
	v_lshl_add_u64 v[74:75], v[82:83], 0, v[22:23]
	global_load_dwordx4 v[16:19], v[26:27], off
	v_lshl_add_u64 v[78:79], v[84:85], 0, v[22:23]
	global_load_dwordx4 v[74:77], v[74:75], off
	v_fmac_f32_e32 v90, v14, v14
	global_load_dwordx4 v[78:81], v[78:79], off
	v_fmac_f32_e32 v90, v15, v15
	v_fmac_f32_e32 v90, v8, v8
	v_fmac_f32_e32 v90, v9, v9
	v_fmac_f32_e32 v90, v10, v10
	v_fmac_f32_e32 v90, v11, v11
	v_fmac_f32_e32 v90, v4, v4
	v_fmac_f32_e32 v90, v5, v5
	v_fmac_f32_e32 v90, v6, v6
	v_pk_mul_f32 v[88:89], v[0:1], v[0:1]
	v_fmac_f32_e32 v90, v7, v7
	v_add_f32_e32 v88, v88, v90
	v_pk_mul_f32 v[86:87], v[2:3], v[2:3]
	v_add_f32_e32 v88, v89, v88
	v_add_f32_e32 v86, v86, v88
	v_add_f32_e32 v86, v87, v86
	v_mov_b32_e32 v88, v86
	s_nop 1
	v_add_f32_dpp v88, v88, v88 quad_perm:[1,0,3,2] row_mask:0xf bank_mask:0xf bound_ctrl:1
	s_nop 1
	v_add_f32_dpp v88, v88, v88 quad_perm:[2,3,0,1] row_mask:0xf bank_mask:0xf bound_ctrl:1
	s_nop 1
	v_add_f32_dpp v88, v88, v88 row_half_mirror row_mask:0xf bank_mask:0xf bound_ctrl:1
	s_nop 1
	v_add_f32_dpp v88, v88, v88 row_mirror row_mask:0xf bank_mask:0xf bound_ctrl:1
	v_mov_b32_e32 v87, v88
	s_nop 1
	v_permlane16_swap_b32_e32 v87, v88
	s_nop 1
	v_add_f32_e32 v88, v87, v88
	v_mov_b32_e32 v87, v88
	s_nop 1
	v_permlane32_swap_b32_e32 v87, v88
	s_nop 1
	v_add_f32_e32 v88, v87, v88
	v_lshl_add_u64 v[86:87], v[50:51], 0, v[34:35]
	v_add_co_u32_e64 v86, s[8:9], s84, v86
	v_fmamk_f32 v88, v88, 0x3a800000, v21
	v_mul_f32_e32 v89, 0x4b800000, v88
	v_cmp_gt_f32_e32 vcc, s82, v88
	v_addc_co_u32_e64 v87, s[8:9], 0, v87, s[8:9]
	s_nop 0
	v_cndmask_b32_e32 v88, v88, v89, vcc
	v_rsq_f32_e32 v90, v88
	v_lshl_add_u64 v[88:89], v[82:83], 0, v[42:43]
	v_mul_f32_e32 v91, 0x45800000, v90
	v_cndmask_b32_e32 v90, v90, v91, vcc
	v_pk_mul_f32 v[12:13], v[12:13], v[90:91] op_sel_hi:[1,0]
	v_pk_mul_f32 v[14:15], v[14:15], v[90:91] op_sel_hi:[1,0]
	v_pk_mul_f32 v[8:9], v[8:9], v[90:91] op_sel_hi:[1,0]
	v_pk_mul_f32 v[10:11], v[10:11], v[90:91] op_sel_hi:[1,0]
	v_pk_mul_f32 v[4:5], v[4:5], v[90:91] op_sel_hi:[1,0]
	v_pk_mul_f32 v[6:7], v[6:7], v[90:91] op_sel_hi:[1,0]
	v_pk_mul_f32 v[0:1], v[0:1], v[90:91] op_sel_hi:[1,0]
	v_pk_mul_f32 v[2:3], v[2:3], v[90:91] op_sel_hi:[1,0]
	s_waitcnt vmcnt(2)
	v_pk_mul_f32 v[12:13], v[16:17], v[12:13]
	v_pk_mul_f32 v[14:15], v[18:19], v[14:15]
	s_waitcnt vmcnt(1)
	v_pk_add_f32 v[16:17], v[74:75], 1.0 op_sel_hi:[1,0]
	v_pk_add_f32 v[18:19], v[76:77], 1.0 op_sel_hi:[1,0]
	s_waitcnt vmcnt(0)
	v_pk_fma_f32 v[12:13], v[16:17], v[12:13], v[78:79]
	v_pk_fma_f32 v[14:15], v[18:19], v[14:15], v[80:81]
	v_cvt_pk_bf16_f32 v12, v12, v13
	v_cvt_pk_bf16_f32 v13, v14, v15
	global_store_dwordx2 v[86:87], v[12:13], off offset:256
	global_load_dwordx4 v[12:15], v[28:29], off
	s_nop 0
	global_load_dwordx4 v[16:19], v[88:89], off
	v_lshl_add_u64 v[74:75], v[84:85], 0, v[42:43]
	global_load_dwordx4 v[74:77], v[74:75], off
	v_lshl_add_u64 v[78:79], v[82:83], 0, v[44:45]
	s_waitcnt vmcnt(2)
	v_pk_mul_f32 v[8:9], v[12:13], v[8:9]
	s_waitcnt vmcnt(1)
	v_pk_add_f32 v[12:13], v[16:17], 1.0 op_sel_hi:[1,0]
	v_pk_mul_f32 v[10:11], v[14:15], v[10:11]
	v_pk_add_f32 v[14:15], v[18:19], 1.0 op_sel_hi:[1,0]
	s_waitcnt vmcnt(0)
	v_pk_fma_f32 v[8:9], v[12:13], v[8:9], v[74:75]
	v_pk_fma_f32 v[10:11], v[14:15], v[10:11], v[76:77]
	v_cvt_pk_bf16_f32 v8, v8, v9
	v_cvt_pk_bf16_f32 v9, v10, v11
	global_store_dwordx2 v[86:87], v[8:9], off offset:768
	global_load_dwordx4 v[8:11], v[30:31], off
	s_nop 0
	global_load_dwordx4 v[12:15], v[78:79], off
	v_lshl_add_u64 v[16:17], v[84:85], 0, v[44:45]
	global_load_dwordx4 v[16:19], v[16:17], off
	v_lshl_add_u64 v[74:75], v[82:83], 0, v[46:47]
	s_waitcnt vmcnt(2)
	v_pk_mul_f32 v[4:5], v[4:5], v[8:9]
	s_waitcnt vmcnt(1)
	v_pk_add_f32 v[8:9], v[12:13], 1.0 op_sel_hi:[1,0]
	v_pk_mul_f32 v[6:7], v[6:7], v[10:11]
	v_pk_add_f32 v[10:11], v[14:15], 1.0 op_sel_hi:[1,0]
	s_waitcnt vmcnt(0)
	v_pk_fma_f32 v[4:5], v[4:5], v[8:9], v[16:17]
	v_pk_fma_f32 v[6:7], v[6:7], v[10:11], v[18:19]
	v_cvt_pk_bf16_f32 v4, v4, v5
	v_cvt_pk_bf16_f32 v5, v6, v7
	global_store_dwordx2 v[86:87], v[4:5], off offset:1280
	global_load_dwordx4 v[4:7], v[32:33], off
	s_nop 0
	global_load_dwordx4 v[8:11], v[74:75], off
	v_lshl_add_u64 v[12:13], v[84:85], 0, v[46:47]
	global_load_dwordx4 v[12:15], v[12:13], off
	s_waitcnt vmcnt(2)
	v_pk_mul_f32 v[0:1], v[0:1], v[4:5]
	s_waitcnt vmcnt(1)
	v_pk_add_f32 v[4:5], v[8:9], 1.0 op_sel_hi:[1,0]
	v_pk_mul_f32 v[2:3], v[2:3], v[6:7]
	v_pk_add_f32 v[6:7], v[10:11], 1.0 op_sel_hi:[1,0]
	s_waitcnt vmcnt(0)
	v_pk_fma_f32 v[0:1], v[0:1], v[4:5], v[12:13]
	v_pk_fma_f32 v[2:3], v[2:3], v[6:7], v[14:15]
	v_cvt_pk_bf16_f32 v0, v0, v1
	v_cvt_pk_bf16_f32 v1, v2, v3
	global_store_dwordx2 v[86:87], v[0:1], off offset:1792
	s_branch .LBB0_1205

.LBB0_1905:
	global_load_dwordx4 v[76:79], v[48:49], off offset:-3072
	global_load_dwordx4 v[16:19], v[48:49], off
	global_load_dwordx4 v[80:83], v[48:49], off offset:-2048
	global_load_dwordx4 v[84:87], v[48:49], off offset:-1024
	v_add_u32_e32 v2, 0xffffe000, v73
	v_lshrrev_b32_e32 v2, 12, v2
	v_add_u32_e32 v2, 11, v2
	v_cmp_lt_i32_e32 vcc, s83, v73
	v_mov_b64_e32 v[0:1], s[4:5]
	v_add_u32_e32 v74, s78, v73
	v_cndmask_b32_e32 v2, 10, v2, vcc
	v_mad_u64_u32 v[0:1], s[8:9], v2, s79, v[0:1]
	v_lshl_add_u64 v[100:101], v[0:1], 0, s[54:55]
	v_lshl_add_u64 v[2:3], v[100:101], 0, v[22:23]
	v_lshl_add_u64 v[102:103], v[0:1], 0, s[56:57]
	global_load_dwordx4 v[88:91], v[2:3], off
	global_load_dwordx4 v[92:95], v[26:27], off
	v_lshl_add_u64 v[0:1], v[102:103], 0, v[22:23]
	global_load_dwordx4 v[96:99], v[0:1], off
	v_cmp_gt_i32_e32 vcc, s79, v74
	v_mov_b32_e32 v43, v23
	v_lshl_add_u64 v[106:107], v[100:101], 0, v[42:43]
	s_waitcnt vmcnt(6)
	v_mul_f32_e32 v4, v77, v77
	v_fmac_f32_e32 v4, v76, v76
	v_fmac_f32_e32 v4, v78, v78
	v_fmac_f32_e32 v4, v79, v79
	s_waitcnt vmcnt(4)
	v_fmac_f32_e32 v4, v80, v80
	v_fmac_f32_e32 v4, v81, v81
	v_fmac_f32_e32 v4, v82, v82
	v_fmac_f32_e32 v4, v83, v83
	s_waitcnt vmcnt(3)
	v_fmac_f32_e32 v4, v84, v84
	v_fmac_f32_e32 v4, v85, v85
	v_fmac_f32_e32 v4, v86, v86
	v_pk_mul_f32 v[2:3], v[16:17], v[16:17]
	v_fmac_f32_e32 v4, v87, v87
	v_add_f32_e32 v2, v2, v4
	v_pk_mul_f32 v[0:1], v[18:19], v[18:19]
	v_add_f32_e32 v2, v3, v2
	v_add_f32_e32 v0, v0, v2
	v_add_f32_e32 v0, v1, v0
	v_mov_b32_e32 v45, v0
	s_nop 1
	v_add_f32_dpp v45, v45, v45 quad_perm:[1,0,3,2] row_mask:0xf bank_mask:0xf bound_ctrl:1
	s_nop 1
	v_add_f32_dpp v45, v45, v45 quad_perm:[2,3,0,1] row_mask:0xf bank_mask:0xf bound_ctrl:1
	s_nop 1
	v_add_f32_dpp v45, v45, v45 row_half_mirror row_mask:0xf bank_mask:0xf bound_ctrl:1
	s_nop 1
	v_add_f32_dpp v45, v45, v45 row_mirror row_mask:0xf bank_mask:0xf bound_ctrl:1
	v_mov_b32_e32 v1, v45
	s_nop 1
	v_permlane16_swap_b32_e32 v1, v45
	s_nop 1
	v_add_f32_e32 v45, v1, v45
	v_mov_b32_e32 v1, v45
	s_nop 1
	v_permlane32_swap_b32_e32 v1, v45
	s_nop 1
	v_add_f32_e32 v45, v1, v45
	v_cndmask_b32_e32 v2, v73, v74, vcc
	s_waitcnt vmcnt(2)
	v_pk_add_f32 v[88:89], v[88:89], 1.0 op_sel_hi:[1,0]
	v_pk_add_f32 v[90:91], v[90:91], 1.0 op_sel_hi:[1,0]
	v_lshl_add_u64 v[0:1], v[52:53], 0, v[34:35]
	v_add_co_u32_e64 v104, s[8:9], s84, v0
	v_addc_co_u32_e64 v105, s[8:9], 0, v1, s[8:9]
	v_ashrrev_i32_e32 v3, 31, v2
	v_lshlrev_b64 v[0:1], 12, v[2:3]
	v_lshl_add_u64 v[0:1], v[24:25], 0, v[0:1]
	global_load_dwordx4 v[12:15], v[0:1], off
	global_load_dwordx4 v[8:11], v[0:1], off offset:1024
	global_load_dwordx4 v[4:7], v[0:1], off offset:2048
	s_nop 0
	global_load_dwordx4 v[0:3], v[0:1], off offset:3072
	v_fmamk_f32 v45, v45, 0x3a800000, v21
	v_mul_f32_e32 v47, 0x4b800000, v45
	v_cmp_gt_f32_e64 s[8:9], s82, v45
	s_nop 1
	v_cndmask_b32_e64 v45, v45, v47, s[8:9]
	v_rsq_f32_e32 v45, v45
	s_nop 0
	v_mul_f32_e32 v47, 0x45800000, v45
	v_cndmask_b32_e64 v108, v45, v47, s[8:9]
	v_pk_mul_f32 v[76:77], v[76:77], v[108:109] op_sel_hi:[1,0]
	v_pk_mul_f32 v[78:79], v[78:79], v[108:109] op_sel_hi:[1,0]
	s_waitcnt vmcnt(5)
	v_pk_mul_f32 v[76:77], v[92:93], v[76:77]
	v_pk_mul_f32 v[78:79], v[94:95], v[78:79]
	s_waitcnt vmcnt(4)
	v_pk_fma_f32 v[76:77], v[88:89], v[76:77], v[96:97]
	v_pk_fma_f32 v[78:79], v[90:91], v[78:79], v[98:99]
	v_cvt_pk_bf16_f32 v76, v76, v77
	v_cvt_pk_bf16_f32 v77, v78, v79
	global_store_dwordx2 v[104:105], v[76:77], off offset:256
	global_load_dwordx4 v[76:79], v[28:29], off
	s_nop 0
	global_load_dwordx4 v[88:91], v[106:107], off
	v_lshl_add_u64 v[92:93], v[102:103], 0, v[42:43]
	global_load_dwordx4 v[92:95], v[92:93], off
	v_pk_mul_f32 v[80:81], v[80:81], v[108:109] op_sel_hi:[1,0]
	v_pk_mul_f32 v[82:83], v[82:83], v[108:109] op_sel_hi:[1,0]
	v_mov_b32_e32 v45, v23
	v_lshl_add_u64 v[96:97], v[100:101], 0, v[44:45]
	v_pk_mul_f32 v[84:85], v[84:85], v[108:109] op_sel_hi:[1,0]
	v_pk_mul_f32 v[86:87], v[86:87], v[108:109] op_sel_hi:[1,0]
	v_mov_b32_e32 v47, v23
	v_pk_mul_f32 v[16:17], v[16:17], v[108:109] op_sel_hi:[1,0]
	v_pk_mul_f32 v[18:19], v[18:19], v[108:109] op_sel_hi:[1,0]
	s_waitcnt vmcnt(2)
	v_pk_mul_f32 v[76:77], v[76:77], v[80:81]
	s_waitcnt vmcnt(1)
	v_pk_add_f32 v[80:81], v[88:89], 1.0 op_sel_hi:[1,0]
	v_pk_mul_f32 v[78:79], v[78:79], v[82:83]
	v_pk_add_f32 v[82:83], v[90:91], 1.0 op_sel_hi:[1,0]
	s_waitcnt vmcnt(0)
	v_pk_fma_f32 v[76:77], v[80:81], v[76:77], v[92:93]
	v_pk_fma_f32 v[78:79], v[82:83], v[78:79], v[94:95]
	v_cvt_pk_bf16_f32 v76, v76, v77
	v_cvt_pk_bf16_f32 v77, v78, v79
	global_store_dwordx2 v[104:105], v[76:77], off offset:768
	global_load_dwordx4 v[76:79], v[30:31], off
	s_nop 0
	global_load_dwordx4 v[80:83], v[96:97], off
	v_lshl_add_u64 v[88:89], v[102:103], 0, v[44:45]
	global_load_dwordx4 v[88:91], v[88:89], off
	v_lshl_add_u64 v[92:93], v[100:101], 0, v[46:47]
	s_waitcnt vmcnt(2)
	v_pk_mul_f32 v[76:77], v[76:77], v[84:85]
	s_waitcnt vmcnt(1)
	v_pk_add_f32 v[80:81], v[80:81], 1.0 op_sel_hi:[1,0]
	v_pk_mul_f32 v[78:79], v[78:79], v[86:87]
	v_pk_add_f32 v[82:83], v[82:83], 1.0 op_sel_hi:[1,0]
	s_waitcnt vmcnt(0)
	v_pk_fma_f32 v[76:77], v[80:81], v[76:77], v[88:89]
	v_pk_fma_f32 v[78:79], v[82:83], v[78:79], v[90:91]
	v_cvt_pk_bf16_f32 v76, v76, v77
	v_cvt_pk_bf16_f32 v77, v78, v79
	global_store_dwordx2 v[104:105], v[76:77], off offset:1280
	global_load_dwordx4 v[76:79], v[32:33], off
	s_nop 0
	global_load_dwordx4 v[80:83], v[92:93], off
	v_lshl_add_u64 v[84:85], v[102:103], 0, v[46:47]
	global_load_dwordx4 v[84:87], v[84:85], off
	s_waitcnt vmcnt(2)
	v_pk_mul_f32 v[16:17], v[76:77], v[16:17]
	s_waitcnt vmcnt(1)
	v_pk_add_f32 v[76:77], v[80:81], 1.0 op_sel_hi:[1,0]
	v_pk_mul_f32 v[18:19], v[78:79], v[18:19]
	v_pk_add_f32 v[78:79], v[82:83], 1.0 op_sel_hi:[1,0]
	s_waitcnt vmcnt(0)
	v_pk_fma_f32 v[16:17], v[76:77], v[16:17], v[84:85]
	v_pk_fma_f32 v[18:19], v[78:79], v[18:19], v[86:87]
	v_cvt_pk_bf16_f32 v16, v16, v17
	v_cvt_pk_bf16_f32 v17, v18, v19
	global_store_dwordx2 v[104:105], v[16:17], off offset:1792
	s_and_saveexec_b64 s[62:63], vcc
	s_cbranch_execz .LBB0_1904
	v_add_u32_e32 v16, 0xffffe000, v74
	v_lshrrev_b32_e32 v16, 12, v16
	v_add_u32_e32 v16, 11, v16
	v_cmp_lt_i32_e32 vcc, s83, v74
	v_mul_f32_e32 v90, v13, v13
	v_fmac_f32_e32 v90, v12, v12
	v_cndmask_b32_e32 v18, 10, v16, vcc
	v_mov_b64_e32 v[16:17], s[4:5]
	v_mad_u64_u32 v[16:17], s[8:9], v18, s79, v[16:17]
	v_lshl_add_u64 v[82:83], v[16:17], 0, s[54:55]
	v_lshl_add_u64 v[84:85], v[16:17], 0, s[56:57]
	v_lshl_add_u64 v[74:75], v[82:83], 0, v[22:23]
	global_load_dwordx4 v[16:19], v[26:27], off
	v_lshl_add_u64 v[78:79], v[84:85], 0, v[22:23]
	global_load_dwordx4 v[74:77], v[74:75], off
	v_fmac_f32_e32 v90, v14, v14
	global_load_dwordx4 v[78:81], v[78:79], off
	v_fmac_f32_e32 v90, v15, v15
	v_fmac_f32_e32 v90, v8, v8
	v_fmac_f32_e32 v90, v9, v9
	v_fmac_f32_e32 v90, v10, v10
	v_fmac_f32_e32 v90, v11, v11
	v_fmac_f32_e32 v90, v4, v4
	v_fmac_f32_e32 v90, v5, v5
	v_fmac_f32_e32 v90, v6, v6
	v_pk_mul_f32 v[88:89], v[0:1], v[0:1]
	v_fmac_f32_e32 v90, v7, v7
	v_add_f32_e32 v88, v88, v90
	v_pk_mul_f32 v[86:87], v[2:3], v[2:3]
	v_add_f32_e32 v88, v89, v88
	v_add_f32_e32 v86, v86, v88
	v_add_f32_e32 v86, v87, v86
	v_mov_b32_e32 v88, v86
	s_nop 1
	v_add_f32_dpp v88, v88, v88 quad_perm:[1,0,3,2] row_mask:0xf bank_mask:0xf bound_ctrl:1
	s_nop 1
	v_add_f32_dpp v88, v88, v88 quad_perm:[2,3,0,1] row_mask:0xf bank_mask:0xf bound_ctrl:1
	s_nop 1
	v_add_f32_dpp v88, v88, v88 row_half_mirror row_mask:0xf bank_mask:0xf bound_ctrl:1
	s_nop 1
	v_add_f32_dpp v88, v88, v88 row_mirror row_mask:0xf bank_mask:0xf bound_ctrl:1
	v_mov_b32_e32 v87, v88
	s_nop 1
	v_permlane16_swap_b32_e32 v87, v88
	s_nop 1
	v_add_f32_e32 v88, v87, v88
	v_mov_b32_e32 v87, v88
	s_nop 1
	v_permlane32_swap_b32_e32 v87, v88
	s_nop 1
	v_add_f32_e32 v88, v87, v88
	v_lshl_add_u64 v[86:87], v[50:51], 0, v[34:35]
	v_add_co_u32_e64 v86, s[8:9], s84, v86
	v_fmamk_f32 v88, v88, 0x3a800000, v21
	v_mul_f32_e32 v89, 0x4b800000, v88
	v_cmp_gt_f32_e32 vcc, s82, v88
	v_addc_co_u32_e64 v87, s[8:9], 0, v87, s[8:9]
	s_nop 0
	v_cndmask_b32_e32 v88, v88, v89, vcc
	v_rsq_f32_e32 v90, v88
	v_lshl_add_u64 v[88:89], v[82:83], 0, v[42:43]
	v_mul_f32_e32 v91, 0x45800000, v90
	v_cndmask_b32_e32 v90, v90, v91, vcc
	v_pk_mul_f32 v[12:13], v[12:13], v[90:91] op_sel_hi:[1,0]
	v_pk_mul_f32 v[14:15], v[14:15], v[90:91] op_sel_hi:[1,0]
	v_pk_mul_f32 v[8:9], v[8:9], v[90:91] op_sel_hi:[1,0]
	v_pk_mul_f32 v[10:11], v[10:11], v[90:91] op_sel_hi:[1,0]
	v_pk_mul_f32 v[4:5], v[4:5], v[90:91] op_sel_hi:[1,0]
	v_pk_mul_f32 v[6:7], v[6:7], v[90:91] op_sel_hi:[1,0]
	v_pk_mul_f32 v[0:1], v[0:1], v[90:91] op_sel_hi:[1,0]
	v_pk_mul_f32 v[2:3], v[2:3], v[90:91] op_sel_hi:[1,0]
	s_waitcnt vmcnt(2)
	v_pk_mul_f32 v[12:13], v[16:17], v[12:13]
	v_pk_mul_f32 v[14:15], v[18:19], v[14:15]
	s_waitcnt vmcnt(1)
	v_pk_add_f32 v[16:17], v[74:75], 1.0 op_sel_hi:[1,0]
	v_pk_add_f32 v[18:19], v[76:77], 1.0 op_sel_hi:[1,0]
	s_waitcnt vmcnt(0)
	v_pk_fma_f32 v[12:13], v[16:17], v[12:13], v[78:79]
	v_pk_fma_f32 v[14:15], v[18:19], v[14:15], v[80:81]
	v_cvt_pk_bf16_f32 v12, v12, v13
	v_cvt_pk_bf16_f32 v13, v14, v15
	global_store_dwordx2 v[86:87], v[12:13], off offset:256
	global_load_dwordx4 v[12:15], v[28:29], off
	s_nop 0
	global_load_dwordx4 v[16:19], v[88:89], off
	v_lshl_add_u64 v[74:75], v[84:85], 0, v[42:43]
	global_load_dwordx4 v[74:77], v[74:75], off
	v_lshl_add_u64 v[78:79], v[82:83], 0, v[44:45]
	s_waitcnt vmcnt(2)
	v_pk_mul_f32 v[8:9], v[12:13], v[8:9]
	s_waitcnt vmcnt(1)
	v_pk_add_f32 v[12:13], v[16:17], 1.0 op_sel_hi:[1,0]
	v_pk_mul_f32 v[10:11], v[14:15], v[10:11]
	v_pk_add_f32 v[14:15], v[18:19], 1.0 op_sel_hi:[1,0]
	s_waitcnt vmcnt(0)
	v_pk_fma_f32 v[8:9], v[12:13], v[8:9], v[74:75]
	v_pk_fma_f32 v[10:11], v[14:15], v[10:11], v[76:77]
	v_cvt_pk_bf16_f32 v8, v8, v9
	v_cvt_pk_bf16_f32 v9, v10, v11
	global_store_dwordx2 v[86:87], v[8:9], off offset:768
	global_load_dwordx4 v[8:11], v[30:31], off
	s_nop 0
	global_load_dwordx4 v[12:15], v[78:79], off
	v_lshl_add_u64 v[16:17], v[84:85], 0, v[44:45]
	global_load_dwordx4 v[16:19], v[16:17], off
	v_lshl_add_u64 v[74:75], v[82:83], 0, v[46:47]
	s_waitcnt vmcnt(2)
	v_pk_mul_f32 v[4:5], v[4:5], v[8:9]
	s_waitcnt vmcnt(1)
	v_pk_add_f32 v[8:9], v[12:13], 1.0 op_sel_hi:[1,0]
	v_pk_mul_f32 v[6:7], v[6:7], v[10:11]
	v_pk_add_f32 v[10:11], v[14:15], 1.0 op_sel_hi:[1,0]
	s_waitcnt vmcnt(0)
	v_pk_fma_f32 v[4:5], v[4:5], v[8:9], v[16:17]
	v_pk_fma_f32 v[6:7], v[6:7], v[10:11], v[18:19]
	v_cvt_pk_bf16_f32 v4, v4, v5
	v_cvt_pk_bf16_f32 v5, v6, v7
	global_store_dwordx2 v[86:87], v[4:5], off offset:1280
	global_load_dwordx4 v[4:7], v[32:33], off
	s_nop 0
	global_load_dwordx4 v[8:11], v[74:75], off
	v_lshl_add_u64 v[12:13], v[84:85], 0, v[46:47]
	global_load_dwordx4 v[12:15], v[12:13], off
	s_waitcnt vmcnt(2)
	v_pk_mul_f32 v[0:1], v[0:1], v[4:5]
	s_waitcnt vmcnt(1)
	v_pk_add_f32 v[4:5], v[8:9], 1.0 op_sel_hi:[1,0]
	v_pk_mul_f32 v[2:3], v[2:3], v[6:7]
	v_pk_add_f32 v[6:7], v[10:11], 1.0 op_sel_hi:[1,0]
	s_waitcnt vmcnt(0)
	v_pk_fma_f32 v[0:1], v[0:1], v[4:5], v[12:13]
	v_pk_fma_f32 v[2:3], v[2:3], v[6:7], v[14:15]
	v_cvt_pk_bf16_f32 v0, v0, v1
	v_cvt_pk_bf16_f32 v1, v2, v3
	global_store_dwordx2 v[86:87], v[0:1], off offset:1792
	s_branch .LBB0_1904

.LBB0_2390:
	global_load_dwordx4 v[76:79], v[48:49], off offset:-3072
	global_load_dwordx4 v[16:19], v[48:49], off
	global_load_dwordx4 v[80:83], v[48:49], off offset:-2048
	global_load_dwordx4 v[84:87], v[48:49], off offset:-1024
	v_add_u32_e32 v2, 0xffffe000, v73
	v_lshrrev_b32_e32 v2, 12, v2
	v_add_u32_e32 v2, 16, v2
	v_cmp_lt_i32_e32 vcc, s83, v73
	v_mov_b64_e32 v[0:1], s[12:13]
	v_add_u32_e32 v74, s78, v73
	v_cndmask_b32_e32 v2, 15, v2, vcc
	v_mad_u64_u32 v[0:1], s[8:9], v2, s79, v[0:1]
	v_lshl_add_u64 v[100:101], v[0:1], 0, s[56:57]
	v_lshl_add_u64 v[2:3], v[100:101], 0, v[22:23]
	v_lshl_add_u64 v[102:103], v[0:1], 0, s[4:5]
	global_load_dwordx4 v[88:91], v[2:3], off
	global_load_dwordx4 v[92:95], v[26:27], off
	v_lshl_add_u64 v[0:1], v[102:103], 0, v[22:23]
	global_load_dwordx4 v[96:99], v[0:1], off
	v_cmp_gt_i32_e32 vcc, s79, v74
	v_mov_b32_e32 v43, v23
	v_lshl_add_u64 v[106:107], v[100:101], 0, v[42:43]
	s_waitcnt vmcnt(6)
	v_mul_f32_e32 v4, v77, v77
	v_fmac_f32_e32 v4, v76, v76
	v_fmac_f32_e32 v4, v78, v78
	v_fmac_f32_e32 v4, v79, v79
	s_waitcnt vmcnt(4)
	v_fmac_f32_e32 v4, v80, v80
	v_fmac_f32_e32 v4, v81, v81
	v_fmac_f32_e32 v4, v82, v82
	v_fmac_f32_e32 v4, v83, v83
	s_waitcnt vmcnt(3)
	v_fmac_f32_e32 v4, v84, v84
	v_fmac_f32_e32 v4, v85, v85
	v_fmac_f32_e32 v4, v86, v86
	v_pk_mul_f32 v[2:3], v[16:17], v[16:17]
	v_fmac_f32_e32 v4, v87, v87
	v_add_f32_e32 v2, v2, v4
	v_pk_mul_f32 v[0:1], v[18:19], v[18:19]
	v_add_f32_e32 v2, v3, v2
	v_add_f32_e32 v0, v0, v2
	v_add_f32_e32 v0, v1, v0
	v_mov_b32_e32 v45, v0
	s_nop 1
	v_add_f32_dpp v45, v45, v45 quad_perm:[1,0,3,2] row_mask:0xf bank_mask:0xf bound_ctrl:1
	s_nop 1
	v_add_f32_dpp v45, v45, v45 quad_perm:[2,3,0,1] row_mask:0xf bank_mask:0xf bound_ctrl:1
	s_nop 1
	v_add_f32_dpp v45, v45, v45 row_half_mirror row_mask:0xf bank_mask:0xf bound_ctrl:1
	s_nop 1
	v_add_f32_dpp v45, v45, v45 row_mirror row_mask:0xf bank_mask:0xf bound_ctrl:1
	v_mov_b32_e32 v1, v45
	s_nop 1
	v_permlane16_swap_b32_e32 v1, v45
	s_nop 1
	v_add_f32_e32 v45, v1, v45
	v_mov_b32_e32 v1, v45
	s_nop 1
	v_permlane32_swap_b32_e32 v1, v45
	s_nop 1
	v_add_f32_e32 v45, v1, v45
	v_cndmask_b32_e32 v2, v73, v74, vcc
	s_waitcnt vmcnt(2)
	v_pk_add_f32 v[88:89], v[88:89], 1.0 op_sel_hi:[1,0]
	v_pk_add_f32 v[90:91], v[90:91], 1.0 op_sel_hi:[1,0]
	v_lshl_add_u64 v[0:1], v[52:53], 0, v[34:35]
	v_add_co_u32_e64 v104, s[8:9], s84, v0
	v_addc_co_u32_e64 v105, s[8:9], 0, v1, s[8:9]
	v_ashrrev_i32_e32 v3, 31, v2
	v_lshlrev_b64 v[0:1], 12, v[2:3]
	v_lshl_add_u64 v[0:1], v[24:25], 0, v[0:1]
	global_load_dwordx4 v[12:15], v[0:1], off
	global_load_dwordx4 v[8:11], v[0:1], off offset:1024
	global_load_dwordx4 v[4:7], v[0:1], off offset:2048
	s_nop 0
	global_load_dwordx4 v[0:3], v[0:1], off offset:3072
	v_fmamk_f32 v45, v45, 0x3a800000, v21
	v_mul_f32_e32 v47, 0x4b800000, v45
	v_cmp_gt_f32_e64 s[8:9], s82, v45
	s_nop 1
	v_cndmask_b32_e64 v45, v45, v47, s[8:9]
	v_rsq_f32_e32 v45, v45
	s_nop 0
	v_mul_f32_e32 v47, 0x45800000, v45
	v_cndmask_b32_e64 v108, v45, v47, s[8:9]
	v_pk_mul_f32 v[76:77], v[76:77], v[108:109] op_sel_hi:[1,0]
	v_pk_mul_f32 v[78:79], v[78:79], v[108:109] op_sel_hi:[1,0]
	s_waitcnt vmcnt(5)
	v_pk_mul_f32 v[76:77], v[92:93], v[76:77]
	v_pk_mul_f32 v[78:79], v[94:95], v[78:79]
	s_waitcnt vmcnt(4)
	v_pk_fma_f32 v[76:77], v[88:89], v[76:77], v[96:97]
	v_pk_fma_f32 v[78:79], v[90:91], v[78:79], v[98:99]
	v_cvt_pk_bf16_f32 v76, v76, v77
	v_cvt_pk_bf16_f32 v77, v78, v79
	global_store_dwordx2 v[104:105], v[76:77], off offset:256
	global_load_dwordx4 v[76:79], v[28:29], off
	s_nop 0
	global_load_dwordx4 v[88:91], v[106:107], off
	v_lshl_add_u64 v[92:93], v[102:103], 0, v[42:43]
	global_load_dwordx4 v[92:95], v[92:93], off
	v_pk_mul_f32 v[80:81], v[80:81], v[108:109] op_sel_hi:[1,0]
	v_pk_mul_f32 v[82:83], v[82:83], v[108:109] op_sel_hi:[1,0]
	v_mov_b32_e32 v45, v23
	v_lshl_add_u64 v[96:97], v[100:101], 0, v[44:45]
	v_pk_mul_f32 v[84:85], v[84:85], v[108:109] op_sel_hi:[1,0]
	v_pk_mul_f32 v[86:87], v[86:87], v[108:109] op_sel_hi:[1,0]
	v_mov_b32_e32 v47, v23
	v_pk_mul_f32 v[16:17], v[16:17], v[108:109] op_sel_hi:[1,0]
	v_pk_mul_f32 v[18:19], v[18:19], v[108:109] op_sel_hi:[1,0]
	s_waitcnt vmcnt(2)
	v_pk_mul_f32 v[76:77], v[76:77], v[80:81]
	s_waitcnt vmcnt(1)
	v_pk_add_f32 v[80:81], v[88:89], 1.0 op_sel_hi:[1,0]
	v_pk_mul_f32 v[78:79], v[78:79], v[82:83]
	v_pk_add_f32 v[82:83], v[90:91], 1.0 op_sel_hi:[1,0]
	s_waitcnt vmcnt(0)
	v_pk_fma_f32 v[76:77], v[80:81], v[76:77], v[92:93]
	v_pk_fma_f32 v[78:79], v[82:83], v[78:79], v[94:95]
	v_cvt_pk_bf16_f32 v76, v76, v77
	v_cvt_pk_bf16_f32 v77, v78, v79
	global_store_dwordx2 v[104:105], v[76:77], off offset:768
	global_load_dwordx4 v[76:79], v[30:31], off
	s_nop 0
	global_load_dwordx4 v[80:83], v[96:97], off
	v_lshl_add_u64 v[88:89], v[102:103], 0, v[44:45]
	global_load_dwordx4 v[88:91], v[88:89], off
	v_lshl_add_u64 v[92:93], v[100:101], 0, v[46:47]
	s_waitcnt vmcnt(2)
	v_pk_mul_f32 v[76:77], v[76:77], v[84:85]
	s_waitcnt vmcnt(1)
	v_pk_add_f32 v[80:81], v[80:81], 1.0 op_sel_hi:[1,0]
	v_pk_mul_f32 v[78:79], v[78:79], v[86:87]
	v_pk_add_f32 v[82:83], v[82:83], 1.0 op_sel_hi:[1,0]
	s_waitcnt vmcnt(0)
	v_pk_fma_f32 v[76:77], v[80:81], v[76:77], v[88:89]
	v_pk_fma_f32 v[78:79], v[82:83], v[78:79], v[90:91]
	v_cvt_pk_bf16_f32 v76, v76, v77
	v_cvt_pk_bf16_f32 v77, v78, v79
	global_store_dwordx2 v[104:105], v[76:77], off offset:1280
	global_load_dwordx4 v[76:79], v[32:33], off
	s_nop 0
	global_load_dwordx4 v[80:83], v[92:93], off
	v_lshl_add_u64 v[84:85], v[102:103], 0, v[46:47]
	global_load_dwordx4 v[84:87], v[84:85], off
	s_waitcnt vmcnt(2)
	v_pk_mul_f32 v[16:17], v[76:77], v[16:17]
	s_waitcnt vmcnt(1)
	v_pk_add_f32 v[76:77], v[80:81], 1.0 op_sel_hi:[1,0]
	v_pk_mul_f32 v[18:19], v[78:79], v[18:19]
	v_pk_add_f32 v[78:79], v[82:83], 1.0 op_sel_hi:[1,0]
	s_waitcnt vmcnt(0)
	v_pk_fma_f32 v[16:17], v[76:77], v[16:17], v[84:85]
	v_pk_fma_f32 v[18:19], v[78:79], v[18:19], v[86:87]
	v_cvt_pk_bf16_f32 v16, v16, v17
	v_cvt_pk_bf16_f32 v17, v18, v19
	global_store_dwordx2 v[104:105], v[16:17], off offset:1792
	s_and_saveexec_b64 s[62:63], vcc
	s_cbranch_execz .LBB0_2389
	v_add_u32_e32 v16, 0xffffe000, v74
	v_lshrrev_b32_e32 v16, 12, v16
	v_add_u32_e32 v16, 16, v16
	v_cmp_lt_i32_e32 vcc, s83, v74
	v_mul_f32_e32 v90, v13, v13
	v_fmac_f32_e32 v90, v12, v12
	v_cndmask_b32_e32 v18, 15, v16, vcc
	v_mov_b64_e32 v[16:17], s[12:13]
	v_mad_u64_u32 v[16:17], s[8:9], v18, s79, v[16:17]
	v_lshl_add_u64 v[82:83], v[16:17], 0, s[56:57]
	v_lshl_add_u64 v[84:85], v[16:17], 0, s[4:5]
	v_lshl_add_u64 v[74:75], v[82:83], 0, v[22:23]
	global_load_dwordx4 v[16:19], v[26:27], off
	v_lshl_add_u64 v[78:79], v[84:85], 0, v[22:23]
	global_load_dwordx4 v[74:77], v[74:75], off
	v_fmac_f32_e32 v90, v14, v14
	global_load_dwordx4 v[78:81], v[78:79], off
	v_fmac_f32_e32 v90, v15, v15
	v_fmac_f32_e32 v90, v8, v8
	v_fmac_f32_e32 v90, v9, v9
	v_fmac_f32_e32 v90, v10, v10
	v_fmac_f32_e32 v90, v11, v11
	v_fmac_f32_e32 v90, v4, v4
	v_fmac_f32_e32 v90, v5, v5
	v_fmac_f32_e32 v90, v6, v6
	v_pk_mul_f32 v[88:89], v[0:1], v[0:1]
	v_fmac_f32_e32 v90, v7, v7
	v_add_f32_e32 v88, v88, v90
	v_pk_mul_f32 v[86:87], v[2:3], v[2:3]
	v_add_f32_e32 v88, v89, v88
	v_add_f32_e32 v86, v86, v88
	v_add_f32_e32 v86, v87, v86
	v_mov_b32_e32 v88, v86
	s_nop 1
	v_add_f32_dpp v88, v88, v88 quad_perm:[1,0,3,2] row_mask:0xf bank_mask:0xf bound_ctrl:1
	s_nop 1
	v_add_f32_dpp v88, v88, v88 quad_perm:[2,3,0,1] row_mask:0xf bank_mask:0xf bound_ctrl:1
	s_nop 1
	v_add_f32_dpp v88, v88, v88 row_half_mirror row_mask:0xf bank_mask:0xf bound_ctrl:1
	s_nop 1
	v_add_f32_dpp v88, v88, v88 row_mirror row_mask:0xf bank_mask:0xf bound_ctrl:1
	v_mov_b32_e32 v87, v88
	s_nop 1
	v_permlane16_swap_b32_e32 v87, v88
	s_nop 1
	v_add_f32_e32 v88, v87, v88
	v_mov_b32_e32 v87, v88
	s_nop 1
	v_permlane32_swap_b32_e32 v87, v88
	s_nop 1
	v_add_f32_e32 v88, v87, v88
	v_lshl_add_u64 v[86:87], v[50:51], 0, v[34:35]
	v_add_co_u32_e64 v86, s[8:9], s84, v86
	v_fmamk_f32 v88, v88, 0x3a800000, v21
	v_mul_f32_e32 v89, 0x4b800000, v88
	v_cmp_gt_f32_e32 vcc, s82, v88
	v_addc_co_u32_e64 v87, s[8:9], 0, v87, s[8:9]
	s_nop 0
	v_cndmask_b32_e32 v88, v88, v89, vcc
	v_rsq_f32_e32 v90, v88
	v_lshl_add_u64 v[88:89], v[82:83], 0, v[42:43]
	v_mul_f32_e32 v91, 0x45800000, v90
	v_cndmask_b32_e32 v90, v90, v91, vcc
	v_pk_mul_f32 v[12:13], v[12:13], v[90:91] op_sel_hi:[1,0]
	v_pk_mul_f32 v[14:15], v[14:15], v[90:91] op_sel_hi:[1,0]
	v_pk_mul_f32 v[8:9], v[8:9], v[90:91] op_sel_hi:[1,0]
	v_pk_mul_f32 v[10:11], v[10:11], v[90:91] op_sel_hi:[1,0]
	v_pk_mul_f32 v[4:5], v[4:5], v[90:91] op_sel_hi:[1,0]
	v_pk_mul_f32 v[6:7], v[6:7], v[90:91] op_sel_hi:[1,0]
	v_pk_mul_f32 v[0:1], v[0:1], v[90:91] op_sel_hi:[1,0]
	v_pk_mul_f32 v[2:3], v[2:3], v[90:91] op_sel_hi:[1,0]
	s_waitcnt vmcnt(2)
	v_pk_mul_f32 v[12:13], v[16:17], v[12:13]
	v_pk_mul_f32 v[14:15], v[18:19], v[14:15]
	s_waitcnt vmcnt(1)
	v_pk_add_f32 v[16:17], v[74:75], 1.0 op_sel_hi:[1,0]
	v_pk_add_f32 v[18:19], v[76:77], 1.0 op_sel_hi:[1,0]
	s_waitcnt vmcnt(0)
	v_pk_fma_f32 v[12:13], v[16:17], v[12:13], v[78:79]
	v_pk_fma_f32 v[14:15], v[18:19], v[14:15], v[80:81]
	v_cvt_pk_bf16_f32 v12, v12, v13
	v_cvt_pk_bf16_f32 v13, v14, v15
	global_store_dwordx2 v[86:87], v[12:13], off offset:256
	global_load_dwordx4 v[12:15], v[28:29], off
	s_nop 0
	global_load_dwordx4 v[16:19], v[88:89], off
	v_lshl_add_u64 v[74:75], v[84:85], 0, v[42:43]
	global_load_dwordx4 v[74:77], v[74:75], off
	v_lshl_add_u64 v[78:79], v[82:83], 0, v[44:45]
	s_waitcnt vmcnt(2)
	v_pk_mul_f32 v[8:9], v[12:13], v[8:9]
	s_waitcnt vmcnt(1)
	v_pk_add_f32 v[12:13], v[16:17], 1.0 op_sel_hi:[1,0]
	v_pk_mul_f32 v[10:11], v[14:15], v[10:11]
	v_pk_add_f32 v[14:15], v[18:19], 1.0 op_sel_hi:[1,0]
	s_waitcnt vmcnt(0)
	v_pk_fma_f32 v[8:9], v[12:13], v[8:9], v[74:75]
	v_pk_fma_f32 v[10:11], v[14:15], v[10:11], v[76:77]
	v_cvt_pk_bf16_f32 v8, v8, v9
	v_cvt_pk_bf16_f32 v9, v10, v11
	global_store_dwordx2 v[86:87], v[8:9], off offset:768
	global_load_dwordx4 v[8:11], v[30:31], off
	s_nop 0
	global_load_dwordx4 v[12:15], v[78:79], off
	v_lshl_add_u64 v[16:17], v[84:85], 0, v[44:45]
	global_load_dwordx4 v[16:19], v[16:17], off
	v_lshl_add_u64 v[74:75], v[82:83], 0, v[46:47]
	s_waitcnt vmcnt(2)
	v_pk_mul_f32 v[4:5], v[4:5], v[8:9]
	s_waitcnt vmcnt(1)
	v_pk_add_f32 v[8:9], v[12:13], 1.0 op_sel_hi:[1,0]
	v_pk_mul_f32 v[6:7], v[6:7], v[10:11]
	v_pk_add_f32 v[10:11], v[14:15], 1.0 op_sel_hi:[1,0]
	s_waitcnt vmcnt(0)
	v_pk_fma_f32 v[4:5], v[4:5], v[8:9], v[16:17]
	v_pk_fma_f32 v[6:7], v[6:7], v[10:11], v[18:19]
	v_cvt_pk_bf16_f32 v4, v4, v5
	v_cvt_pk_bf16_f32 v5, v6, v7
	global_store_dwordx2 v[86:87], v[4:5], off offset:1280
	global_load_dwordx4 v[4:7], v[32:33], off
	s_nop 0
	global_load_dwordx4 v[8:11], v[74:75], off
	v_lshl_add_u64 v[12:13], v[84:85], 0, v[46:47]
	global_load_dwordx4 v[12:15], v[12:13], off
	s_waitcnt vmcnt(2)
	v_pk_mul_f32 v[0:1], v[0:1], v[4:5]
	s_waitcnt vmcnt(1)
	v_pk_add_f32 v[4:5], v[8:9], 1.0 op_sel_hi:[1,0]
	v_pk_mul_f32 v[2:3], v[2:3], v[6:7]
	v_pk_add_f32 v[6:7], v[10:11], 1.0 op_sel_hi:[1,0]
	s_waitcnt vmcnt(0)
	v_pk_fma_f32 v[0:1], v[0:1], v[4:5], v[12:13]
	v_pk_fma_f32 v[2:3], v[2:3], v[6:7], v[14:15]
	v_cvt_pk_bf16_f32 v0, v0, v1
	v_cvt_pk_bf16_f32 v1, v2, v3
	global_store_dwordx2 v[86:87], v[0:1], off offset:1792
	s_branch .LBB0_2389
